# v96 + context-row phase work moved from workgroups 0-63 to 64-127 (the QKV tail workgroups 0-15 are the critical path and now start QKV without it)
# speedup vs baseline: 1.0058x; 1.0058x over previous
; __device__ __forceinline__ unsigned pk2(float lo, float hi) { return pg8::cvt_pk_bf16(lo, hi); }
; __device__ __forceinline__ float bf_lo(unsigned w) { return __uint_as_float(w << 16); }
; __device__ __forceinline__ float bf_hi(unsigned w) { return __uint_as_float(w & 0xffff0000u); }
; #define CACC  WSP(float, WS_G)
; #define SSQ    WSP(float, WS_SSQ)
; __global__ void __launch_bounds__(NWAVES * 64, 2) fwd_kernel(Args args) {
;     ...
;                 const float* wg = ng0 + 2 * DM; const float* wsc = modl + 3 * 6144 + 1024 + 2 * 6144;
;                 for (int r = gw; r < MCTX; r += NGW) { const f32x4* xr = (const f32x4*)(CACC + (size_t)r * DM) + lane; unsigned long long* h8 = (unsigned long long*)(H16 + (size_t)(MLAT + r) * DM) + lane; f32x4 v[4]; float ss = 0.f;
; #pragma unroll
;                     for (int j = 0; j < 4; ++j) { const unsigned long long hw_ = h8[64 * j]; const unsigned lo_ = (unsigned)hw_, hi_ = (unsigned)(hw_ >> 32);
;                         v[j] = (f32x4){bf_lo(lo_), bf_hi(lo_), bf_lo(hi_), bf_hi(hi_)} + ((xr[64 * j] + xr[64 * j + MCTX * DM / 4]) + (xr[64 * j + 2 * (MCTX * DM / 4)] + xr[64 * j + 3 * (MCTX * DM / 4)]));
;                         h8[64 * j] = (unsigned long long)pk2(v[j][0], v[j][1]) | ((unsigned long long)pk2(v[j][2], v[j][3]) << 32);
;                         ss += (v[j][0] * v[j][0] + v[j][1] * v[j][1]) + (v[j][2] * v[j][2] + v[j][3] * v[j][3]); }
;                     ss = wave_sum(ss); if (lane < 16) SSQ[(size_t)(MLAT + r) * 16 + lane] = lane == 0 ? ss : 0.f;
;                     unsigned long long* o8 = (unsigned long long*)(AB + (size_t)(MLAT + r) * DM) + lane;
.LBB0_223:
	s_andn2_b64 vcc, exec, s[0:1]
	s_cbranch_vccnz .LBB0_158
	s_waitcnt vmcnt(0)
	v_mov_b32_e32 v0, v215
	s_mov_b32 s1, s82
	s_mov_b32 s2, s84
	s_lshl_b32 s2, s2, 3
	v_readfirstlane_b32 s0, v0
	s_ashr_i32 s0, s0, 6
	s_add_i32 s0, s2, s0
	s_waitcnt lgkmcnt(0)
	s_mov_b64 s[12:13], s[94:95]
	s_sub_i32 s0, s0, 0x200
	s_cmpk_gt_u32 s0, 0x1ff
	s_cbranch_scc1 .LBB0_229
	s_load_dwordx2 s[6:7], s[12:13], 0xb8
	s_load_dwordx2 s[4:5], s[12:13], 0x30
	v_and_b32_e32 v6, 63, v0
	v_lshlrev_b32_e32 v8, 4, v6
	v_mov_b32_e32 v9, v213
	s_waitcnt lgkmcnt(0)
	v_lshl_add_u64 v[2:3], s[6:7], 0, v[8:9]
	v_lshl_add_u64 v[0:1], s[4:5], 0, v[8:9]
	s_mov_b64 s[4:5], 0x2000
	v_lshl_add_u64 v[0:1], v[0:1], 0, s[4:5]
	s_mov_b64 s[4:5], 0x1f000
	v_lshl_add_u64 v[2:3], v[2:3], 0, s[4:5]
	s_add_i32 s4, s0, 0x4000
	s_ashr_i32 s5, s4, 31
	s_lshl_b32 s2, s1, 3
	s_lshl_b64 s[12:13], s[4:5], 6
	s_add_u32 s12, s12, 0x14000000
	s_addc_u32 s13, s13, 0
	s_lshl_b64 s[4:5], s[4:5], 11
	s_ashr_i32 s1, s0, 31
	v_cmp_gt_u32_e64 s[38:39], 16, v6
	v_cmp_eq_u32_e64 s[40:41], 0, v6
	v_lshlrev_b32_e32 v212, 2, v6
	s_ashr_i32 s3, s2, 31
	v_lshl_or_b32 v6, v6, 3, s4
	v_mov_b32_e32 v7, s5
	s_lshl_b64 s[4:5], s[0:1], 12
	v_lshl_add_u64 v[4:5], s[12:13], 0, v[212:213]
	s_lshl_b64 s[12:13], s[2:3], 6
	s_lshl_b64 s[14:15], s[2:3], 11
	v_or_b32_e32 v8, s4, v8
	v_mov_b32_e32 v9, s5
	s_lshl_b64 s[18:19], s[2:3], 12
	s_branch .LBB0_227
